# out-proj epilogue rewritten by hand (row-folded full-line loads/stores, prefetched residual, DPP/permlane row reduction); only 16 copy workers during out-proj
# baseline (speedup 1.0000x reference)
_Z10fwd_kernel6Params:
	s_mov_b32 s98, 0
	s_mov_b64 s[100:101], s[0:1]
	s_mov_b32 s99, s2
	s_load_dwordx4 s[40:43], s[0:1], 0x98
	v_and_b32_e32 v156, 0x3ff, v0
	v_cmp_eq_u32_e64 s[36:37], 0, v156
	s_and_saveexec_b64 s[4:5], s[36:37]
	s_cbranch_execz .LBB0_2
	s_add_i32 s3, 0, 0x252e0
	v_mov_b32_e32 v1, 0
	v_mov_b32_e32 v2, s3
	s_add_i32 s3, 0, 0x252e4
	ds_write_b32 v2, v1
	v_mov_b32_e32 v2, s3
	ds_write_b32 v2, v1
.LBB0_2:
	s_or_b64 exec, exec, s[4:5]
	s_waitcnt lgkmcnt(0)
	s_mov_b32 s43, 4
	s_barrier
	s_getreg_b32 s3, hwreg(HW_REG_XCC_ID, 0, 4)
	s_and_saveexec_b64 s[4:5], s[36:37]
	s_cbranch_execz .LBB0_5
	s_mov_b64 s[6:7], exec
	v_mbcnt_lo_u32_b32 v1, s6, 0
	v_mbcnt_hi_u32_b32 v1, s7, v1
	v_cmp_eq_u32_e32 vcc, 0, v1
	s_and_b64 s[8:9], exec, vcc
	s_mov_b64 exec, s[8:9]
	s_cbranch_execz .LBB0_5
	s_lshl_b32 s3, s3, 8
	s_and_b32 s3, s3, 0xf00
	s_add_u32 s8, s40, s3
	s_addc_u32 s9, s41, 0
	s_bcnt1_i32_b64 s3, s[6:7]
	v_mov_b32_e32 v1, 0x6331000
	v_mov_b32_e32 v2, s3
	global_atomic_add v1, v2, s[8:9] offset:768

.Lprobe_reentry:
	s_cmp_lt_i32 s42, 1
	s_cselect_b64 s[8:9], -1, 0
	s_cmp_gt_i32 s43, 0
	s_cselect_b64 s[4:5], -1, 0
	s_and_b64 s[4:5], s[8:9], s[4:5]
	s_andn2_b64 vcc, exec, s[4:5]
	s_cbranch_vccnz .LBB0_206
	s_cmp_gt_i32 s42, -1
	s_cbranch_scc1 .LBB0_60
	s_getreg_b32 s3, hwreg(HW_REG_XCC_ID, 0, 4)
	s_waitcnt vmcnt(0)
	s_barrier
	s_and_saveexec_b64 s[4:5], s[36:37]
	s_cbranch_execz .LBB0_59
	s_add_i32 s6, 0, 0x252e0
	v_mov_b32_e32 v1, s6
	s_waitcnt vmcnt(0) expcnt(0) lgkmcnt(0)
	ds_read_b32 v3, v1
	s_add_i32 s6, 0, 0x252e4
	v_mov_b32_e32 v1, s6
	ds_read_b32 v1, v1
	s_and_b32 s3, s3, 15
	s_waitcnt lgkmcnt(1)
	v_cmp_ne_u32_e32 vcc, 0, v3
	s_cbranch_vccnz .LBB0_23
	s_load_dwordx2 s[12:13], s[0:1], 0xa8
	s_load_dword s11, s[0:1], 0xb0
	s_add_u32 s6, s40, 0x6331100
	s_addc_u32 s7, s41, 0
	s_add_u32 s10, s40, 0x6331300
	s_waitcnt lgkmcnt(0)
	s_mul_i32 s33, s13, s12
	s_mul_i32 s33, s33, s11
	s_addc_u32 s11, s41, 0
	s_add_u32 s12, s40, 0x6331400
	s_addc_u32 s13, s41, 0
	s_add_u32 s14, s40, 0x6331500
	s_addc_u32 s15, s41, 0
	s_add_u32 s16, s40, 0x6331600
	s_addc_u32 s17, s41, 0
	s_add_u32 s18, s40, 0x6331700
	s_addc_u32 s19, s41, 0
	s_add_u32 s20, s40, 0x6331800
	s_addc_u32 s21, s41, 0
	s_add_u32 s22, s40, 0x6331900
	s_addc_u32 s23, s41, 0
	s_add_u32 s24, s40, 0x6331a00
	s_addc_u32 s25, s41, 0
	s_add_u32 s26, s40, 0x6331b00
	s_addc_u32 s27, s41, 0
	s_add_u32 s28, s40, 0x6331c00
	s_addc_u32 s29, s41, 0
	s_add_u32 s30, s40, 0x6331d00
	s_addc_u32 s31, s41, 0
	s_add_u32 s34, s40, 0x6331e00
	s_addc_u32 s35, s41, 0
	s_add_u32 s38, s40, 0x6331f00
	s_addc_u32 s39, s41, 0
	s_add_u32 s44, s40, 0x6332000
	s_addc_u32 s45, s41, 0
	s_add_u32 s46, s40, 0x6332100
	s_addc_u32 s47, s41, 0
	s_add_u32 s48, s40, 0x6332200
	s_addc_u32 s49, s41, 0
	s_mov_b32 s56, 1
	v_mov_b32_e32 v17, 0
	s_branch .LBB0_11

.LBB0_627:
	s_cmp_lt_i32 s2, 32
	s_cselect_b64 s[48:49], -1, 0
	s_and_b64 vcc, exec, s[48:49]
	v_bfe_u32 v134, v156, 2, 2
	v_lshrrev_b32_e32 v96, 7, v156
	s_cmp_eq_u32 s98, 0
	s_cbranch_scc1 .LBB0_648
	s_cbranch_vccnz .LBB0_648
	s_add_u32 s50, s40, 0x6330c00
	s_movk_i32 s3, 0x100
	s_addc_u32 s51, s41, 0
	v_cmp_gt_u32_e64 s[4:5], s3, v156
	v_lshlrev_b32_e32 v0, 4, v156
	s_add_i32 s3, 0, 0x13400
	v_and_b32_e32 v7, 0x7f, v156
	v_lshlrev_b32_e32 v8, 2, v156
	v_add_u32_e32 v11, s3, v0
	v_lshl_add_u32 v13, v96, 10, s3
	s_add_i32 s3, 0, 0x14400
	v_and_b32_e32 v4, 31, v156
	v_add_u32_e32 v15, s3, v8
	v_lshl_add_u32 v56, v7, 2, s3
	s_movk_i32 s3, 0x80
	v_lshlrev_b32_e32 v2, 3, v4
	v_lshl_add_u32 v5, v4, 4, 0
	v_add_u32_e32 v4, 0x200, v156
	v_cmp_gt_u32_e64 s[6:7], s3, v156
	s_movk_i32 s3, 0xff
	v_lshrrev_b32_e32 v12, 5, v4
	v_add_u32_e32 v4, 0x600, v156
	v_cmp_lt_u32_e64 s[8:9], s3, v156
	s_movk_i32 s3, 0x17f
	v_lshrrev_b32_e32 v16, 5, v4
	v_lshlrev_b32_e32 v18, 4, v96
	v_cmp_lt_u32_e64 s[10:11], s3, v156
	s_movk_i32 s3, 0x1ff
	v_mul_u32_u24_e32 v4, 0x880, v96
	v_cmp_lt_u32_e64 s[12:13], s3, v156
	v_or_b32_e32 v4, v4, v7
	v_or_b32_e32 v20, 2, v18
	s_movk_i32 s3, 0x88
	v_bfe_u32 v3, v156, 4, 2
	v_lshrrev_b32_e32 v10, 5, v156
	v_lshl_add_u32 v57, v4, 1, 0
	v_mad_u32_u24 v4, v20, s3, v7
	v_and_b32_e32 v6, 15, v156
	v_lshl_add_u32 v58, v4, 1, 0
	v_and_b32_e32 v34, 2, v10
	v_lshlrev_b32_e32 v4, 2, v3
	v_lshlrev_b32_e32 v48, 4, v3
	v_or_b32_e32 v35, v4, v18
	v_or_b32_e32 v38, v18, v6
	v_add_u32_e32 v54, 0, v48
	s_movk_i32 s3, 0x110
	v_lshl_or_b32 v36, v34, 4, v6
	v_lshrrev_b32_e32 v1, 6, v156
	v_mad_u32_u24 v65, v38, s3, v54
	v_cmp_le_u32_e64 s[14:15], v34, v96
	s_add_i32 s3, 0, 0x11000
	v_or_b32_e32 v37, 1, v35
	v_or_b32_e32 v39, 2, v35
	v_or_b32_e32 v40, 3, v35
	v_cmp_lt_u32_e64 s[24:25], v34, v96
	v_or_b32_e32 v34, 16, v36
	s_add_i32 s38, 0, 0x8800
	v_cmp_gt_u32_e64 s[16:17], v36, v35
	v_mul_u32_u24_e32 v81, 0x90, v35
	v_cmp_gt_u32_e64 s[26:27], v34, v35
	v_lshlrev_b32_e32 v35, 1, v34
	v_cmp_gt_u32_e64 s[28:29], v34, v37
	v_cmp_gt_u32_e64 s[30:31], v34, v39
	v_cmp_gt_u32_e64 s[34:35], v34, v40
	v_lshlrev_b32_e32 v34, 5, v1
	v_and_b32_e32 v1, 12, v8
	s_cmp_lg_u32 s38, -1
	v_add3_u32 v66, s3, v81, v35
	v_lshl_or_b32 v3, v3, 3, v134
	v_or_b32_e32 v35, v34, v1
	s_cselect_b32 s38, s38, 0
	s_movk_i32 s33, 0x220
	v_mul_u32_u24_e32 v55, 0x110, v36
	v_lshl_add_u32 v80, v36, 1, s3
	v_cmp_gt_u32_e64 s[18:19], v36, v37
	v_cmp_gt_u32_e64 s[20:21], v36, v39
	v_cmp_gt_u32_e64 s[22:23], v36, v40
	v_lshl_add_u32 v36, v35, 1, s38
	v_or_b32_e32 v40, 32, v3
	v_mad_u32_u24 v70, v3, s33, v36
	v_mad_u32_u24 v71, v40, s33, v36
	v_or_b32_e32 v36, 16, v34
	v_or_b32_e32 v1, v36, v1
	v_lshl_add_u32 v1, v1, 1, s38
	v_mul_u32_u24_e32 v38, 0x90, v38
	v_mov_b32_e32 v9, 0
	v_mul_u32_u24_e32 v39, 0x220, v3
	v_mad_u32_u24 v72, v3, s33, v1
	v_mad_u32_u24 v73, v40, s33, v1
	v_bfe_u32 v1, v156, 6, 1
	v_lshlrev_b32_e32 v3, 3, v156
	v_add3_u32 v74, s3, v38, v48
	s_add_u32 s3, s40, 0x6330d00
	v_lshlrev_b32_e32 v40, 8, v1
	v_and_b32_e32 v3, 24, v3
	v_lshlrev_b32_e32 v52, 7, v1
	s_addc_u32 s33, s41, 0
	v_mov_b32_e32 v1, v9
	v_add_u32_e32 v3, s38, v3
	s_add_u32 s54, s40, 0x16838f00
	v_lshl_add_u64 v[0:1], s[40:41], 0, v[0:1]
	s_mov_b64 s[38:39], 0x16734f00
	v_add3_u32 v75, v3, v40, v39
	s_addc_u32 s55, s41, 0
	v_lshl_add_u64 v[38:39], v[0:1], 0, s[38:39]
	v_lshlrev_b32_e32 v0, 1, v7
	v_mov_b32_e32 v1, v9
	v_lshl_add_u64 v[42:43], s[40:41], 0, v[8:9]
	s_mov_b64 s[38:39], 0x356d8f00
	s_load_dwordx4 s[44:47], s[0:1], 0x40
	v_lshl_add_u64 v[40:41], s[54:55], 0, v[0:1]
	v_lshl_add_u64 v[42:43], v[42:43], 0, s[38:39]
	v_lshl_add_u64 v[0:1], s[40:41], 0, v[0:1]
	s_mov_b64 s[38:39], 0x316d8f00
	v_lshlrev_b32_e32 v8, 7, v7
	v_lshl_add_u64 v[44:45], v[0:1], 0, s[38:39]
	v_lshl_add_u64 v[0:1], s[40:41], 0, v[8:9]
	v_lshlrev_b32_e32 v8, 5, v96
	v_lshl_add_u64 v[0:1], v[0:1], 0, v[8:9]
	s_mov_b64 s[38:39], 0x326d8f00
	v_mov_b32_e32 v49, v9
	v_mul_u32_u24_e32 v50, 0x220, v10
	v_mul_u32_u24_e32 v51, 0x220, v12
	v_mul_u32_u24_e32 v53, 0x220, v16
	v_lshl_add_u64 v[46:47], v[0:1], 0, s[38:39]
	s_add_u32 s56, s40, 0x23358f00
	v_lshl_add_u64 v[0:1], s[40:41], 0, v[48:49]
	s_mov_b64 s[38:39], 0x336d8f00
	s_mov_b32 s53, 0
	v_or_b32_e32 v14, 32, v10
	v_mov_b32_e32 v17, v9
	v_mov_b32_e32 v19, v9
	v_mov_b32_e32 v21, v9
	v_or_b32_e32 v22, 4, v18
	v_add_u32_e32 v59, 0x220, v58
	v_mov_b32_e32 v23, v9
	v_or_b32_e32 v24, 6, v18
	v_add_u32_e32 v60, 0x440, v58
	v_mov_b32_e32 v25, v9
	v_or_b32_e32 v26, 8, v18
	v_add_u32_e32 v61, 0x660, v58
	v_mov_b32_e32 v27, v9
	v_or_b32_e32 v28, 10, v18
	v_add_u32_e32 v62, 0x880, v58
	v_mov_b32_e32 v29, v9
	v_or_b32_e32 v30, 12, v18
	v_add_u32_e32 v63, 0xaa0, v58
	v_mov_b32_e32 v31, v9
	v_or_b32_e32 v32, 14, v18
	v_add_u32_e32 v64, 0xcc0, v58
	v_mov_b32_e32 v33, v9
	v_add_u32_e32 v67, 0x90, v66
	v_add_u32_e32 v68, 0x120, v66
	v_add_u32_e32 v69, 0x1b0, v66
	s_mov_b32 s52, -1
	v_mov_b32_e32 v35, v9
	v_mov_b32_e32 v37, v9
	v_add_u32_e32 v76, 0x4400, v75
	s_addc_u32 s57, s41, 0
	v_lshl_add_u64 v[48:49], v[0:1], 0, s[38:39]
	s_add_i32 s62, 0, 0x252f0
	s_movk_i32 s63, 0x3ff
	s_movk_i32 s64, 0x3000
	s_movk_i32 s65, 0x6000
	s_movk_i32 s66, 0x3200
	v_lshlrev_b32_e32 v8, 1, v2
	v_add_u32_e32 v77, v5, v50
	v_add_u32_e32 v78, v5, v51
	v_add_u32_e32 v79, v5, v53
	s_mov_b32 s67, 0x9000
	s_mov_b32 s68, 0xc000
	s_mov_b32 s69, 0xf000
	s_mov_b32 s70, 0x12000
	s_mov_b32 s71, 0x13000
	s_mov_b32 s72, 0x15000
	s_mov_b32 s73, 0x16000
	s_mov_b32 s74, 0x19000
	s_mov_b32 s75, 0x1c000
	s_mov_b32 s76, 0x1f000
	s_mov_b32 s77, 0x22000
	s_mov_b32 s78, 0x25000
	s_mov_b32 s79, 0x28000
	s_mov_b32 s80, 0x2b000
	s_mov_b32 s81, 0x2c000
	s_mov_b32 s82, 0x2e000
	s_mov_b32 s83, 0x2f000
	s_mov_b32 s84, 0xbfb8aa3b
	s_mov_b32 s85, 0x800000
	s_mov_b32 s86, 0x3f317217
	s_mov_b32 s87, 0x7f800000
	s_mov_b32 s88, 0x3d800000
	v_add_u32_e32 v80, v80, v81
	v_lshlrev_b32_e32 v50, 2, v4
	v_lshlrev_b32_e32 v52, 2, v52
	v_mov_b32_e32 v81, 0x41b17218
	v_add_u32_e32 v82, v54, v55
	s_branch .LBB0_631

.LBB0_648:
	s_mov_b64 s[4:5], -1
	s_and_b64 vcc, exec, s[48:49]
	s_waitcnt vmcnt(0) lgkmcnt(0)
	s_barrier
	s_cbranch_vccz .LBB0_700
	s_cmp_eq_u32 s98, 0
	s_cbranch_scc1 .LBB0_924
	s_bfe_u32 s28, s2, 0x20001
	s_ashr_i32 s6, s2, 3
	s_and_saveexec_b64 s[4:5], s[36:37]
	s_cbranch_execz .LBB0_662
	s_lshl_b32 s3, s6, 5
	s_lshl_b32 s7, s28, 3
	s_or_b32 s8, s7, s3
	s_ashr_i32 s9, s8, 31
	s_lshl_b64 s[8:9], s[8:9], 2
	s_add_u32 s8, s40, s8
	s_addc_u32 s9, s41, s9
	v_mov_b32_e32 v0, 0x6330000
	global_load_dword v0, v0, s[8:9] offset:3328 sc1
	s_add_u32 s8, s8, 0x6330d00
	s_addc_u32 s9, s9, 0
	s_waitcnt vmcnt(0)
	v_cmp_lt_u32_e32 vcc, 7, v0
	s_cbranch_vccnz .LBB0_661
	s_mov_b32 s3, 0xffff8
	v_mov_b32_e32 v0, 0
	s_branch .LBB0_653

.Lprobe_tramp:
	s_branch .Lprobe_reentry
.LBB0_924:
	s_cmp_eq_u32 s98, 0
	s_cbranch_scc1 .LBB0_981
	s_add_u32 s28, s40, 0x6330c40
	s_addc_u32 s29, s41, 0
	s_and_saveexec_b64 s[4:5], s[36:37]
	s_cbranch_execz .LBB0_928
	s_mov_b64 s[8:9], exec
	v_mbcnt_lo_u32_b32 v0, s8, 0
	v_mbcnt_hi_u32_b32 v0, s9, v0
	v_cmp_eq_u32_e32 vcc, 0, v0
	s_and_saveexec_b64 s[6:7], vcc
	s_cbranch_execz .LBB0_927
	s_bcnt1_i32_b64 s3, s[8:9]
	v_mov_b32_e32 v1, 0
	v_mov_b32_e32 v2, s3
	global_atomic_add v1, v1, v2, s[28:29] sc0

.LBB0_1886:
	s_mov_b64 exec, -1
	s_cmp_lg_u32 s98, 0
	s_cbranch_scc1 .Lprobe_end
	s_mov_b32 s98, 1
	s_mov_b64 s[0:1], s[100:101]
	s_mov_b32 s2, s99
	s_load_dwordx4 s[40:43], s[0:1], 0x98
	s_load_dword s9, s[0:1], 0xa8
	s_waitcnt vmcnt(0) lgkmcnt(0)
	s_barrier
	s_and_saveexec_b64 s[4:5], s[36:37]
	s_cbranch_execz .Lprobe_join
	buffer_wbl2 sc1
	s_waitcnt vmcnt(0)
	s_add_u32 s6, s40, 0x6334700
	s_addc_u32 s7, s41, 0
	v_mov_b32_e32 v1, 0
	v_mov_b32_e32 v2, 1
	global_atomic_add v1, v2, s[6:7]
	s_waitcnt vmcnt(0)
.Lprobe_spin:
	global_load_dword v3, v1, s[6:7] sc1
	s_waitcnt vmcnt(0)
	v_readfirstlane_b32 s8, v3
	s_nop 3
	s_cmp_ge_u32 s8, s9
	s_cbranch_scc1 .Lprobe_spun
	s_sleep 2
	s_branch .Lprobe_spin

.Lprobe_join:
	s_or_b64 exec, exec, s[4:5]
	s_barrier
	s_branch .Lprobe_tramp
